# P2d re-scan loads of AF / gelu (their last use) also marked nt, on top of v11
# speedup vs baseline: 1.0306x; 1.0004x over previous
; __device__ __forceinline__ float bf_lo(unsigned w) { return __uint_as_float(w << 16); }
; __device__ __forceinline__ float bf_hi(unsigned w) { return __uint_as_float(w & 0xffff0000u); }
; __global__ void __launch_bounds__(NTHR, 2) hybrid_block_fwd(Args a) {
;     ...
;         const int c2 = gtid & 1023, chunk = (gtid >> 10) & (NCH - 1), b = gtid >> 16;
;         f32x2 H = (f32x2){0.f, 0.f};
; #pragma unroll 4
;         for (int j = 0; j < chunk; ++j) { const f32x2 P = ((const f32x2*)(AGGP + (size_t)(b * NCH + j) * LW))[c2], Hj = ((const f32x2*)(AGGH + (size_t)(b * NCH + j) * LW))[c2]; H = P * H + Hj; }
;         const size_t r0 = (size_t)b * SEQ + (size_t)chunk * CH_L;
;         const u32x2* pab = (const u32x2*)((const unsigned*)AF + r0 * LW) + c2;
;         const unsigned* pg = (const unsigned*)(GELU_U + r0 * LW) + c2; unsigned* po = (unsigned*)(YCAT + r0 * KC + PW) + c2;
; #pragma unroll 16
;         for (int i = 0; i < CH_L; ++i) {
;             const u32x2 q = pab[(size_t)i * (LW / 2)]; const f32x2 av = (f32x2){__builtin_amdgcn_exp2f(bf_lo(q.x)), __builtin_amdgcn_exp2f(bf_lo(q.y))}, bv = (f32x2){bf_hi(q.x), bf_hi(q.y)}; const unsigned gq = pg[(size_t)i * (LW / 2)];
.LBB0_669:
	s_or_b64 exec, exec, s[8:9]
	s_waitcnt lgkmcnt(0)
	v_mov_b32_e32 v0, v212
	v_readlane_b32 s8, v248, 8
	s_barrier
	v_add_u32_e32 v1, s8, v0
	v_and_b32_e32 v1, 0x3ff, v1
	v_lshlrev_b32_e32 v2, 3, v1
	v_lshlrev_b32_e32 v3, 2, v1
	v_add_u32_e32 v6, 0x100000, v2
	s_lshr_b32 s9, s8, 10
	s_and_b32 s10, s9, 63
	s_lshr_b32 s11, s9, 6
	s_lshl_b32 s21, s9, 20
	s_add_u32 s12, s92, s21
	s_addc_u32 s13, s93, 0
	s_lshl_b32 s21, s9, 19
	s_add_u32 s14, s94, s21
	s_addc_u32 s15, s95, 0
	s_add_u32 s14, s14, 0x9f00000
	s_addc_u32 s15, s15, 0
	s_mul_i32 s21, s9, 0xc0000
	s_add_u32 s18, s94, s21
	s_addc_u32 s19, s95, 0
	s_add_u32 s18, s18, 0x15f00800
	s_addc_u32 s19, s19, 0
	s_lshl_b32 s21, s11, 19
	s_add_u32 s0, s94, s21
	s_addc_u32 s1, s95, 0
	s_add_u32 s0, s0, 0x100000
	s_addc_u32 s1, s1, 0
	global_load_dwordx2 v[32:33], v2, s[12:13] nt
	global_load_dword v64, v3, s[14:15] nt
	s_add_u32 s12, s12, 0x2000
	s_addc_u32 s13, s13, 0
	s_add_u32 s14, s14, 0x1000
	s_addc_u32 s15, s15, 0
	global_load_dwordx2 v[34:35], v2, s[12:13] nt
	global_load_dword v65, v3, s[14:15] nt
	s_add_u32 s12, s12, 0x2000
	s_addc_u32 s13, s13, 0
	s_add_u32 s14, s14, 0x1000
	s_addc_u32 s15, s15, 0
	global_load_dwordx2 v[36:37], v2, s[12:13] nt
	global_load_dword v66, v3, s[14:15] nt
	s_add_u32 s12, s12, 0x2000
	s_addc_u32 s13, s13, 0
	s_add_u32 s14, s14, 0x1000
	s_addc_u32 s15, s15, 0
	global_load_dwordx2 v[38:39], v2, s[12:13] nt
	global_load_dword v67, v3, s[14:15] nt
	s_add_u32 s12, s12, 0x2000
	s_addc_u32 s13, s13, 0
	s_add_u32 s14, s14, 0x1000
	s_addc_u32 s15, s15, 0
	global_load_dwordx2 v[40:41], v2, s[12:13] nt
	global_load_dword v68, v3, s[14:15] nt
	s_add_u32 s12, s12, 0x2000
	s_addc_u32 s13, s13, 0
	s_add_u32 s14, s14, 0x1000
	s_addc_u32 s15, s15, 0
	global_load_dwordx2 v[42:43], v2, s[12:13] nt
	global_load_dword v69, v3, s[14:15] nt
	s_add_u32 s12, s12, 0x2000
	s_addc_u32 s13, s13, 0
	s_add_u32 s14, s14, 0x1000
	s_addc_u32 s15, s15, 0
	global_load_dwordx2 v[44:45], v2, s[12:13] nt
	global_load_dword v70, v3, s[14:15] nt
	s_add_u32 s12, s12, 0x2000
	s_addc_u32 s13, s13, 0
	s_add_u32 s14, s14, 0x1000
	s_addc_u32 s15, s15, 0
	global_load_dwordx2 v[46:47], v2, s[12:13] nt
	global_load_dword v71, v3, s[14:15] nt
	s_add_u32 s12, s12, 0x2000
	s_addc_u32 s13, s13, 0
	s_add_u32 s14, s14, 0x1000
	s_addc_u32 s15, s15, 0
	global_load_dwordx2 v[48:49], v2, s[12:13] nt
	global_load_dword v72, v3, s[14:15] nt
	s_add_u32 s12, s12, 0x2000
	s_addc_u32 s13, s13, 0
	s_add_u32 s14, s14, 0x1000
	s_addc_u32 s15, s15, 0
	global_load_dwordx2 v[50:51], v2, s[12:13] nt
	global_load_dword v73, v3, s[14:15] nt
	s_add_u32 s12, s12, 0x2000
	s_addc_u32 s13, s13, 0
	s_add_u32 s14, s14, 0x1000
	s_addc_u32 s15, s15, 0
	global_load_dwordx2 v[52:53], v2, s[12:13] nt
	global_load_dword v74, v3, s[14:15] nt
	s_add_u32 s12, s12, 0x2000
	s_addc_u32 s13, s13, 0
	s_add_u32 s14, s14, 0x1000
	s_addc_u32 s15, s15, 0
	global_load_dwordx2 v[54:55], v2, s[12:13] nt
	global_load_dword v75, v3, s[14:15] nt
	s_add_u32 s12, s12, 0x2000
	s_addc_u32 s13, s13, 0
	s_add_u32 s14, s14, 0x1000
	s_addc_u32 s15, s15, 0
	global_load_dwordx2 v[56:57], v2, s[12:13] nt
	global_load_dword v76, v3, s[14:15] nt
	s_add_u32 s12, s12, 0x2000
	s_addc_u32 s13, s13, 0
	s_add_u32 s14, s14, 0x1000
	s_addc_u32 s15, s15, 0
	global_load_dwordx2 v[58:59], v2, s[12:13] nt
	global_load_dword v77, v3, s[14:15] nt
	s_add_u32 s12, s12, 0x2000
	s_addc_u32 s13, s13, 0
	s_add_u32 s14, s14, 0x1000
	s_addc_u32 s15, s15, 0
	global_load_dwordx2 v[60:61], v2, s[12:13] nt
	global_load_dword v78, v3, s[14:15] nt
	s_add_u32 s12, s12, 0x2000
	s_addc_u32 s13, s13, 0
	s_add_u32 s14, s14, 0x1000
	s_addc_u32 s15, s15, 0
	global_load_dwordx2 v[62:63], v2, s[12:13] nt
	global_load_dword v79, v3, s[14:15] nt
	s_add_u32 s12, s12, 0x2000
	s_addc_u32 s13, s13, 0
	s_add_u32 s14, s14, 0x1000
	s_addc_u32 s15, s15, 0
	v_mov_b32_e32 v4, 0
	v_mov_b32_e32 v5, 0
	s_cmp_eq_u32 s10, 0
	s_cbranch_scc1 .Lp2d_prefix_done

; __device__ __forceinline__ unsigned cvt_pk_bf16(float lo, float hi) { unsigned r; asm volatile("v_cvt_pk_bf16_f32 %0, %1, %2" : "=v"(r) : "v"(lo), "v"(hi)); return r; }
; __device__ __forceinline__ float bf_lo(unsigned w) { return __uint_as_float(w << 16); }
; __device__ __forceinline__ float bf_hi(unsigned w) { return __uint_as_float(w & 0xffff0000u); }
; __global__ void __launch_bounds__(NTHR, 2) hybrid_block_fwd(Args a) {
;     ...
;         for (int i = 0; i < CH_L; ++i) {
;             const u32x2 q = pab[(size_t)i * (LW / 2)]; const f32x2 av = (f32x2){__builtin_amdgcn_exp2f(bf_lo(q.x)), __builtin_amdgcn_exp2f(bf_lo(q.y))}, bv = (f32x2){bf_hi(q.x), bf_hi(q.y)}; const unsigned gq = pg[(size_t)i * (LW / 2)];
;             H = av * H + bv;
;             po[(size_t)i * (KC / 2)] = cvt_pk_bf16(H.x * bf_lo(gq), H.y * bf_hi(gq));
;         }
.Lp2d_prefix_done:
	s_waitcnt vmcnt(30)
	v_lshlrev_b32_e32 v8, 16, v32
	v_lshlrev_b32_e32 v9, 16, v33
	v_exp_f32_e32 v8, v8
	v_exp_f32_e32 v9, v9
	v_and_b32_e32 v10, 0xffff0000, v32
	v_and_b32_e32 v11, 0xffff0000, v33
	v_lshlrev_b32_e32 v12, 16, v64
	v_and_b32_e32 v13, 0xffff0000, v64
	v_pk_fma_f32 v[4:5], v[4:5], v[8:9], v[10:11]
	v_mul_f32_e32 v12, v4, v12
	v_mul_f32_e32 v13, v5, v13
	v_cvt_pk_bf16_f32 v12, v12, v13
	global_store_dword v3, v12, s[18:19]
	s_add_u32 s18, s18, 0x1800
	s_addc_u32 s19, s19, 0
	global_load_dwordx2 v[32:33], v2, s[12:13] nt
	global_load_dword v64, v3, s[14:15] nt
	s_add_u32 s12, s12, 0x2000
	s_addc_u32 s13, s13, 0
	s_add_u32 s14, s14, 0x1000
	s_addc_u32 s15, s15, 0
	s_waitcnt vmcnt(31)
	v_lshlrev_b32_e32 v16, 16, v34
	v_lshlrev_b32_e32 v17, 16, v35
	v_exp_f32_e32 v16, v16
	v_exp_f32_e32 v17, v17
	v_and_b32_e32 v18, 0xffff0000, v34
	v_and_b32_e32 v19, 0xffff0000, v35
	v_lshlrev_b32_e32 v20, 16, v65
	v_and_b32_e32 v21, 0xffff0000, v65
	v_pk_fma_f32 v[4:5], v[4:5], v[16:17], v[18:19]
	v_mul_f32_e32 v20, v4, v20
	v_mul_f32_e32 v21, v5, v21
	v_cvt_pk_bf16_f32 v20, v20, v21
	global_store_dword v3, v20, s[18:19]
	s_add_u32 s18, s18, 0x1800
	s_addc_u32 s19, s19, 0
	global_load_dwordx2 v[34:35], v2, s[12:13] nt
	global_load_dword v65, v3, s[14:15] nt
	s_add_u32 s12, s12, 0x2000
	s_addc_u32 s13, s13, 0
	s_add_u32 s14, s14, 0x1000
	s_addc_u32 s15, s15, 0
	s_waitcnt vmcnt(32)
	v_lshlrev_b32_e32 v8, 16, v36
	v_lshlrev_b32_e32 v9, 16, v37
	v_exp_f32_e32 v8, v8
	v_exp_f32_e32 v9, v9
	v_and_b32_e32 v10, 0xffff0000, v36
	v_and_b32_e32 v11, 0xffff0000, v37
	v_lshlrev_b32_e32 v12, 16, v66
	v_and_b32_e32 v13, 0xffff0000, v66
	v_pk_fma_f32 v[4:5], v[4:5], v[8:9], v[10:11]
	v_mul_f32_e32 v12, v4, v12
	v_mul_f32_e32 v13, v5, v13
	v_cvt_pk_bf16_f32 v12, v12, v13
	global_store_dword v3, v12, s[18:19]
	s_add_u32 s18, s18, 0x1800
	s_addc_u32 s19, s19, 0
	global_load_dwordx2 v[36:37], v2, s[12:13] nt
	global_load_dword v66, v3, s[14:15] nt
	s_add_u32 s12, s12, 0x2000
	s_addc_u32 s13, s13, 0
	s_add_u32 s14, s14, 0x1000
	s_addc_u32 s15, s15, 0
	s_waitcnt vmcnt(33)
	v_lshlrev_b32_e32 v16, 16, v38
	v_lshlrev_b32_e32 v17, 16, v39
	v_exp_f32_e32 v16, v16
	v_exp_f32_e32 v17, v17
	v_and_b32_e32 v18, 0xffff0000, v38
	v_and_b32_e32 v19, 0xffff0000, v39
	v_lshlrev_b32_e32 v20, 16, v67
	v_and_b32_e32 v21, 0xffff0000, v67
	v_pk_fma_f32 v[4:5], v[4:5], v[16:17], v[18:19]
	v_mul_f32_e32 v20, v4, v20
	v_mul_f32_e32 v21, v5, v21
	v_cvt_pk_bf16_f32 v20, v20, v21
	global_store_dword v3, v20, s[18:19]
	s_add_u32 s18, s18, 0x1800
	s_addc_u32 s19, s19, 0
	global_load_dwordx2 v[38:39], v2, s[12:13] nt
	global_load_dword v67, v3, s[14:15] nt
	s_add_u32 s12, s12, 0x2000
	s_addc_u32 s13, s13, 0
	s_add_u32 s14, s14, 0x1000
	s_addc_u32 s15, s15, 0
	s_waitcnt vmcnt(34)
	v_lshlrev_b32_e32 v8, 16, v40
	v_lshlrev_b32_e32 v9, 16, v41
	v_exp_f32_e32 v8, v8
	v_exp_f32_e32 v9, v9
	v_and_b32_e32 v10, 0xffff0000, v40
	v_and_b32_e32 v11, 0xffff0000, v41
	v_lshlrev_b32_e32 v12, 16, v68
	v_and_b32_e32 v13, 0xffff0000, v68
	v_pk_fma_f32 v[4:5], v[4:5], v[8:9], v[10:11]
	v_mul_f32_e32 v12, v4, v12
	v_mul_f32_e32 v13, v5, v13
	v_cvt_pk_bf16_f32 v12, v12, v13
	global_store_dword v3, v12, s[18:19]
	s_add_u32 s18, s18, 0x1800
	s_addc_u32 s19, s19, 0
	global_load_dwordx2 v[40:41], v2, s[12:13] nt
	global_load_dword v68, v3, s[14:15] nt
	s_add_u32 s12, s12, 0x2000
	s_addc_u32 s13, s13, 0
	s_add_u32 s14, s14, 0x1000
	s_addc_u32 s15, s15, 0
	s_waitcnt vmcnt(35)
	v_lshlrev_b32_e32 v16, 16, v42
	v_lshlrev_b32_e32 v17, 16, v43
	v_exp_f32_e32 v16, v16
	v_exp_f32_e32 v17, v17
	v_and_b32_e32 v18, 0xffff0000, v42
	v_and_b32_e32 v19, 0xffff0000, v43
	v_lshlrev_b32_e32 v20, 16, v69
	v_and_b32_e32 v21, 0xffff0000, v69
	v_pk_fma_f32 v[4:5], v[4:5], v[16:17], v[18:19]
	v_mul_f32_e32 v20, v4, v20
	v_mul_f32_e32 v21, v5, v21
	v_cvt_pk_bf16_f32 v20, v20, v21
	global_store_dword v3, v20, s[18:19]
	s_add_u32 s18, s18, 0x1800
	s_addc_u32 s19, s19, 0
	global_load_dwordx2 v[42:43], v2, s[12:13] nt
	global_load_dword v69, v3, s[14:15] nt
	s_add_u32 s12, s12, 0x2000
	s_addc_u32 s13, s13, 0
	s_add_u32 s14, s14, 0x1000
	s_addc_u32 s15, s15, 0
	s_waitcnt vmcnt(36)
	v_lshlrev_b32_e32 v8, 16, v44
	v_lshlrev_b32_e32 v9, 16, v45
	v_exp_f32_e32 v8, v8
	v_exp_f32_e32 v9, v9
	v_and_b32_e32 v10, 0xffff0000, v44
	v_and_b32_e32 v11, 0xffff0000, v45
	v_lshlrev_b32_e32 v12, 16, v70
	v_and_b32_e32 v13, 0xffff0000, v70
	v_pk_fma_f32 v[4:5], v[4:5], v[8:9], v[10:11]
	v_mul_f32_e32 v12, v4, v12
	v_mul_f32_e32 v13, v5, v13
	v_cvt_pk_bf16_f32 v12, v12, v13
	global_store_dword v3, v12, s[18:19]
	s_add_u32 s18, s18, 0x1800
	s_addc_u32 s19, s19, 0
	global_load_dwordx2 v[44:45], v2, s[12:13] nt
	global_load_dword v70, v3, s[14:15] nt
	s_add_u32 s12, s12, 0x2000
	s_addc_u32 s13, s13, 0
	s_add_u32 s14, s14, 0x1000
	s_addc_u32 s15, s15, 0
	s_waitcnt vmcnt(37)
	v_lshlrev_b32_e32 v16, 16, v46
	v_lshlrev_b32_e32 v17, 16, v47
	v_exp_f32_e32 v16, v16
	v_exp_f32_e32 v17, v17
	v_and_b32_e32 v18, 0xffff0000, v46
	v_and_b32_e32 v19, 0xffff0000, v47
	v_lshlrev_b32_e32 v20, 16, v71
	v_and_b32_e32 v21, 0xffff0000, v71
	v_pk_fma_f32 v[4:5], v[4:5], v[16:17], v[18:19]
	v_mul_f32_e32 v20, v4, v20
	v_mul_f32_e32 v21, v5, v21
	v_cvt_pk_bf16_f32 v20, v20, v21
	global_store_dword v3, v20, s[18:19]
	s_add_u32 s18, s18, 0x1800
	s_addc_u32 s19, s19, 0
	global_load_dwordx2 v[46:47], v2, s[12:13] nt
	global_load_dword v71, v3, s[14:15] nt
	s_add_u32 s12, s12, 0x2000
	s_addc_u32 s13, s13, 0
	s_add_u32 s14, s14, 0x1000
	s_addc_u32 s15, s15, 0
	s_waitcnt vmcnt(38)
; __device__ __forceinline__ unsigned cvt_pk_bf16(float lo, float hi) { unsigned r; asm volatile("v_cvt_pk_bf16_f32 %0, %1, %2" : "=v"(r) : "v"(lo), "v"(hi)); return r; }
; __device__ __forceinline__ float bf_lo(unsigned w) { return __uint_as_float(w << 16); }
; __device__ __forceinline__ float bf_hi(unsigned w) { return __uint_as_float(w & 0xffff0000u); }
; __global__ void __launch_bounds__(NTHR, 2) hybrid_block_fwd(Args a) {
;     ...
;         for (int i = 0; i < CH_L; ++i) {
;             const u32x2 q = pab[(size_t)i * (LW / 2)]; const f32x2 av = (f32x2){__builtin_amdgcn_exp2f(bf_lo(q.x)), __builtin_amdgcn_exp2f(bf_lo(q.y))}, bv = (f32x2){bf_hi(q.x), bf_hi(q.y)}; const unsigned gq = pg[(size_t)i * (LW / 2)];
;             H = av * H + bv;
;             po[(size_t)i * (KC / 2)] = cvt_pk_bf16(H.x * bf_lo(gq), H.y * bf_hi(gq));
;         }
	v_lshlrev_b32_e32 v8, 16, v48
	v_lshlrev_b32_e32 v9, 16, v49
	v_exp_f32_e32 v8, v8
	v_exp_f32_e32 v9, v9
	v_and_b32_e32 v10, 0xffff0000, v48
	v_and_b32_e32 v11, 0xffff0000, v49
	v_lshlrev_b32_e32 v12, 16, v72
	v_and_b32_e32 v13, 0xffff0000, v72
	v_pk_fma_f32 v[4:5], v[4:5], v[8:9], v[10:11]
	v_mul_f32_e32 v12, v4, v12
	v_mul_f32_e32 v13, v5, v13
	v_cvt_pk_bf16_f32 v12, v12, v13
	global_store_dword v3, v12, s[18:19]
	s_add_u32 s18, s18, 0x1800
	s_addc_u32 s19, s19, 0
	global_load_dwordx2 v[48:49], v2, s[12:13] nt
	global_load_dword v72, v3, s[14:15] nt
	s_add_u32 s12, s12, 0x2000
	s_addc_u32 s13, s13, 0
	s_add_u32 s14, s14, 0x1000
	s_addc_u32 s15, s15, 0
	s_waitcnt vmcnt(39)
	v_lshlrev_b32_e32 v16, 16, v50
	v_lshlrev_b32_e32 v17, 16, v51
	v_exp_f32_e32 v16, v16
	v_exp_f32_e32 v17, v17
	v_and_b32_e32 v18, 0xffff0000, v50
	v_and_b32_e32 v19, 0xffff0000, v51
	v_lshlrev_b32_e32 v20, 16, v73
	v_and_b32_e32 v21, 0xffff0000, v73
	v_pk_fma_f32 v[4:5], v[4:5], v[16:17], v[18:19]
	v_mul_f32_e32 v20, v4, v20
	v_mul_f32_e32 v21, v5, v21
	v_cvt_pk_bf16_f32 v20, v20, v21
	global_store_dword v3, v20, s[18:19]
	s_add_u32 s18, s18, 0x1800
	s_addc_u32 s19, s19, 0
	global_load_dwordx2 v[50:51], v2, s[12:13] nt
	global_load_dword v73, v3, s[14:15] nt
	s_add_u32 s12, s12, 0x2000
	s_addc_u32 s13, s13, 0
	s_add_u32 s14, s14, 0x1000
	s_addc_u32 s15, s15, 0
	s_waitcnt vmcnt(40)
	v_lshlrev_b32_e32 v8, 16, v52
	v_lshlrev_b32_e32 v9, 16, v53
	v_exp_f32_e32 v8, v8
	v_exp_f32_e32 v9, v9
	v_and_b32_e32 v10, 0xffff0000, v52
	v_and_b32_e32 v11, 0xffff0000, v53
	v_lshlrev_b32_e32 v12, 16, v74
	v_and_b32_e32 v13, 0xffff0000, v74
	v_pk_fma_f32 v[4:5], v[4:5], v[8:9], v[10:11]
	v_mul_f32_e32 v12, v4, v12
	v_mul_f32_e32 v13, v5, v13
	v_cvt_pk_bf16_f32 v12, v12, v13
	global_store_dword v3, v12, s[18:19]
	s_add_u32 s18, s18, 0x1800
	s_addc_u32 s19, s19, 0
	global_load_dwordx2 v[52:53], v2, s[12:13] nt
	global_load_dword v74, v3, s[14:15] nt
	s_add_u32 s12, s12, 0x2000
	s_addc_u32 s13, s13, 0
	s_add_u32 s14, s14, 0x1000
	s_addc_u32 s15, s15, 0
	s_waitcnt vmcnt(41)
	v_lshlrev_b32_e32 v16, 16, v54
	v_lshlrev_b32_e32 v17, 16, v55
	v_exp_f32_e32 v16, v16
	v_exp_f32_e32 v17, v17
	v_and_b32_e32 v18, 0xffff0000, v54
	v_and_b32_e32 v19, 0xffff0000, v55
	v_lshlrev_b32_e32 v20, 16, v75
	v_and_b32_e32 v21, 0xffff0000, v75
	v_pk_fma_f32 v[4:5], v[4:5], v[16:17], v[18:19]
	v_mul_f32_e32 v20, v4, v20
	v_mul_f32_e32 v21, v5, v21
	v_cvt_pk_bf16_f32 v20, v20, v21
	global_store_dword v3, v20, s[18:19]
	s_add_u32 s18, s18, 0x1800
	s_addc_u32 s19, s19, 0
	global_load_dwordx2 v[54:55], v2, s[12:13] nt
	global_load_dword v75, v3, s[14:15] nt
	s_add_u32 s12, s12, 0x2000
	s_addc_u32 s13, s13, 0
	s_add_u32 s14, s14, 0x1000
	s_addc_u32 s15, s15, 0
	s_waitcnt vmcnt(42)
	v_lshlrev_b32_e32 v8, 16, v56
	v_lshlrev_b32_e32 v9, 16, v57
	v_exp_f32_e32 v8, v8
	v_exp_f32_e32 v9, v9
	v_and_b32_e32 v10, 0xffff0000, v56
	v_and_b32_e32 v11, 0xffff0000, v57
	v_lshlrev_b32_e32 v12, 16, v76
	v_and_b32_e32 v13, 0xffff0000, v76
	v_pk_fma_f32 v[4:5], v[4:5], v[8:9], v[10:11]
	v_mul_f32_e32 v12, v4, v12
	v_mul_f32_e32 v13, v5, v13
	v_cvt_pk_bf16_f32 v12, v12, v13
	global_store_dword v3, v12, s[18:19]
	s_add_u32 s18, s18, 0x1800
	s_addc_u32 s19, s19, 0
	global_load_dwordx2 v[56:57], v2, s[12:13] nt
	global_load_dword v76, v3, s[14:15] nt
	s_add_u32 s12, s12, 0x2000
	s_addc_u32 s13, s13, 0
	s_add_u32 s14, s14, 0x1000
	s_addc_u32 s15, s15, 0
	s_waitcnt vmcnt(43)
	v_lshlrev_b32_e32 v16, 16, v58
	v_lshlrev_b32_e32 v17, 16, v59
	v_exp_f32_e32 v16, v16
	v_exp_f32_e32 v17, v17
	v_and_b32_e32 v18, 0xffff0000, v58
	v_and_b32_e32 v19, 0xffff0000, v59
	v_lshlrev_b32_e32 v20, 16, v77
	v_and_b32_e32 v21, 0xffff0000, v77
	v_pk_fma_f32 v[4:5], v[4:5], v[16:17], v[18:19]
	v_mul_f32_e32 v20, v4, v20
	v_mul_f32_e32 v21, v5, v21
	v_cvt_pk_bf16_f32 v20, v20, v21
	global_store_dword v3, v20, s[18:19]
	s_add_u32 s18, s18, 0x1800
	s_addc_u32 s19, s19, 0
	global_load_dwordx2 v[58:59], v2, s[12:13] nt
	global_load_dword v77, v3, s[14:15] nt
	s_add_u32 s12, s12, 0x2000
	s_addc_u32 s13, s13, 0
	s_add_u32 s14, s14, 0x1000
	s_addc_u32 s15, s15, 0
	s_waitcnt vmcnt(44)
	v_lshlrev_b32_e32 v8, 16, v60
	v_lshlrev_b32_e32 v9, 16, v61
	v_exp_f32_e32 v8, v8
	v_exp_f32_e32 v9, v9
	v_and_b32_e32 v10, 0xffff0000, v60
	v_and_b32_e32 v11, 0xffff0000, v61
	v_lshlrev_b32_e32 v12, 16, v78
	v_and_b32_e32 v13, 0xffff0000, v78
	v_pk_fma_f32 v[4:5], v[4:5], v[8:9], v[10:11]
	v_mul_f32_e32 v12, v4, v12
	v_mul_f32_e32 v13, v5, v13
	v_cvt_pk_bf16_f32 v12, v12, v13
	global_store_dword v3, v12, s[18:19]
	s_add_u32 s18, s18, 0x1800
	s_addc_u32 s19, s19, 0
	global_load_dwordx2 v[60:61], v2, s[12:13] nt
	global_load_dword v78, v3, s[14:15] nt
	s_add_u32 s12, s12, 0x2000
	s_addc_u32 s13, s13, 0
	s_add_u32 s14, s14, 0x1000
	s_addc_u32 s15, s15, 0
	s_waitcnt vmcnt(45)
	v_lshlrev_b32_e32 v16, 16, v62
	v_lshlrev_b32_e32 v17, 16, v63
	v_exp_f32_e32 v16, v16
	v_exp_f32_e32 v17, v17
	v_and_b32_e32 v18, 0xffff0000, v62
	v_and_b32_e32 v19, 0xffff0000, v63
	v_lshlrev_b32_e32 v20, 16, v79
	v_and_b32_e32 v21, 0xffff0000, v79
	v_pk_fma_f32 v[4:5], v[4:5], v[16:17], v[18:19]
	v_mul_f32_e32 v20, v4, v20
	v_mul_f32_e32 v21, v5, v21
	v_cvt_pk_bf16_f32 v20, v20, v21
	global_store_dword v3, v20, s[18:19]
	s_add_u32 s18, s18, 0x1800
	s_addc_u32 s19, s19, 0
	global_load_dwordx2 v[62:63], v2, s[12:13] nt
	global_load_dword v79, v3, s[14:15] nt
	s_add_u32 s12, s12, 0x2000
	s_addc_u32 s13, s13, 0
	s_add_u32 s14, s14, 0x1000
	s_addc_u32 s15, s15, 0
	s_mov_b32 s22, 6
; __device__ __forceinline__ unsigned cvt_pk_bf16(float lo, float hi) { unsigned r; asm volatile("v_cvt_pk_bf16_f32 %0, %1, %2" : "=v"(r) : "v"(lo), "v"(hi)); return r; }
; __device__ __forceinline__ float bf_lo(unsigned w) { return __uint_as_float(w << 16); }
; __device__ __forceinline__ float bf_hi(unsigned w) { return __uint_as_float(w & 0xffff0000u); }
; __global__ void __launch_bounds__(NTHR, 2) hybrid_block_fwd(Args a) {
;     ...
;         for (int i = 0; i < CH_L; ++i) {
;             const u32x2 q = pab[(size_t)i * (LW / 2)]; const f32x2 av = (f32x2){__builtin_amdgcn_exp2f(bf_lo(q.x)), __builtin_amdgcn_exp2f(bf_lo(q.y))}, bv = (f32x2){bf_hi(q.x), bf_hi(q.y)}; const unsigned gq = pg[(size_t)i * (LW / 2)];
;             H = av * H + bv;
;             po[(size_t)i * (KC / 2)] = cvt_pk_bf16(H.x * bf_lo(gq), H.y * bf_hi(gq));
;         }
.Lp2d_steady:
	s_waitcnt vmcnt(45)
	v_lshlrev_b32_e32 v8, 16, v32
	v_lshlrev_b32_e32 v9, 16, v33
	v_exp_f32_e32 v8, v8
	v_exp_f32_e32 v9, v9
	v_and_b32_e32 v10, 0xffff0000, v32
	v_and_b32_e32 v11, 0xffff0000, v33
	v_lshlrev_b32_e32 v12, 16, v64
	v_and_b32_e32 v13, 0xffff0000, v64
	v_pk_fma_f32 v[4:5], v[4:5], v[8:9], v[10:11]
	v_mul_f32_e32 v12, v4, v12
	v_mul_f32_e32 v13, v5, v13
	v_cvt_pk_bf16_f32 v12, v12, v13
	global_store_dword v3, v12, s[18:19]
	s_add_u32 s18, s18, 0x1800
	s_addc_u32 s19, s19, 0
	global_load_dwordx2 v[32:33], v2, s[12:13] nt
	global_load_dword v64, v3, s[14:15] nt
	s_add_u32 s12, s12, 0x2000
	s_addc_u32 s13, s13, 0
	s_add_u32 s14, s14, 0x1000
	s_addc_u32 s15, s15, 0
	s_waitcnt vmcnt(45)
	v_lshlrev_b32_e32 v16, 16, v34
	v_lshlrev_b32_e32 v17, 16, v35
	v_exp_f32_e32 v16, v16
	v_exp_f32_e32 v17, v17
	v_and_b32_e32 v18, 0xffff0000, v34
	v_and_b32_e32 v19, 0xffff0000, v35
	v_lshlrev_b32_e32 v20, 16, v65
	v_and_b32_e32 v21, 0xffff0000, v65
	v_pk_fma_f32 v[4:5], v[4:5], v[16:17], v[18:19]
	v_mul_f32_e32 v20, v4, v20
	v_mul_f32_e32 v21, v5, v21
	v_cvt_pk_bf16_f32 v20, v20, v21
	global_store_dword v3, v20, s[18:19]
	s_add_u32 s18, s18, 0x1800
	s_addc_u32 s19, s19, 0
	global_load_dwordx2 v[34:35], v2, s[12:13] nt
	global_load_dword v65, v3, s[14:15] nt
	s_add_u32 s12, s12, 0x2000
	s_addc_u32 s13, s13, 0
	s_add_u32 s14, s14, 0x1000
	s_addc_u32 s15, s15, 0
	s_waitcnt vmcnt(45)
	v_lshlrev_b32_e32 v8, 16, v36
	v_lshlrev_b32_e32 v9, 16, v37
	v_exp_f32_e32 v8, v8
	v_exp_f32_e32 v9, v9
	v_and_b32_e32 v10, 0xffff0000, v36
	v_and_b32_e32 v11, 0xffff0000, v37
	v_lshlrev_b32_e32 v12, 16, v66
	v_and_b32_e32 v13, 0xffff0000, v66
	v_pk_fma_f32 v[4:5], v[4:5], v[8:9], v[10:11]
	v_mul_f32_e32 v12, v4, v12
	v_mul_f32_e32 v13, v5, v13
	v_cvt_pk_bf16_f32 v12, v12, v13
	global_store_dword v3, v12, s[18:19]
	s_add_u32 s18, s18, 0x1800
	s_addc_u32 s19, s19, 0
	global_load_dwordx2 v[36:37], v2, s[12:13] nt
	global_load_dword v66, v3, s[14:15] nt
	s_add_u32 s12, s12, 0x2000
	s_addc_u32 s13, s13, 0
	s_add_u32 s14, s14, 0x1000
	s_addc_u32 s15, s15, 0
	s_waitcnt vmcnt(45)
	v_lshlrev_b32_e32 v16, 16, v38
	v_lshlrev_b32_e32 v17, 16, v39
	v_exp_f32_e32 v16, v16
	v_exp_f32_e32 v17, v17
	v_and_b32_e32 v18, 0xffff0000, v38
	v_and_b32_e32 v19, 0xffff0000, v39
	v_lshlrev_b32_e32 v20, 16, v67
	v_and_b32_e32 v21, 0xffff0000, v67
	v_pk_fma_f32 v[4:5], v[4:5], v[16:17], v[18:19]
	v_mul_f32_e32 v20, v4, v20
	v_mul_f32_e32 v21, v5, v21
	v_cvt_pk_bf16_f32 v20, v20, v21
	global_store_dword v3, v20, s[18:19]
	s_add_u32 s18, s18, 0x1800
	s_addc_u32 s19, s19, 0
	global_load_dwordx2 v[38:39], v2, s[12:13] nt
	global_load_dword v67, v3, s[14:15] nt
	s_add_u32 s12, s12, 0x2000
	s_addc_u32 s13, s13, 0
	s_add_u32 s14, s14, 0x1000
	s_addc_u32 s15, s15, 0
	s_waitcnt vmcnt(45)
	v_lshlrev_b32_e32 v8, 16, v40
	v_lshlrev_b32_e32 v9, 16, v41
	v_exp_f32_e32 v8, v8
	v_exp_f32_e32 v9, v9
	v_and_b32_e32 v10, 0xffff0000, v40
	v_and_b32_e32 v11, 0xffff0000, v41
	v_lshlrev_b32_e32 v12, 16, v68
	v_and_b32_e32 v13, 0xffff0000, v68
	v_pk_fma_f32 v[4:5], v[4:5], v[8:9], v[10:11]
	v_mul_f32_e32 v12, v4, v12
	v_mul_f32_e32 v13, v5, v13
	v_cvt_pk_bf16_f32 v12, v12, v13
	global_store_dword v3, v12, s[18:19]
	s_add_u32 s18, s18, 0x1800
	s_addc_u32 s19, s19, 0
	global_load_dwordx2 v[40:41], v2, s[12:13] nt
	global_load_dword v68, v3, s[14:15] nt
	s_add_u32 s12, s12, 0x2000
	s_addc_u32 s13, s13, 0
	s_add_u32 s14, s14, 0x1000
	s_addc_u32 s15, s15, 0
	s_waitcnt vmcnt(45)
	v_lshlrev_b32_e32 v16, 16, v42
	v_lshlrev_b32_e32 v17, 16, v43
	v_exp_f32_e32 v16, v16
	v_exp_f32_e32 v17, v17
	v_and_b32_e32 v18, 0xffff0000, v42
	v_and_b32_e32 v19, 0xffff0000, v43
	v_lshlrev_b32_e32 v20, 16, v69
	v_and_b32_e32 v21, 0xffff0000, v69
	v_pk_fma_f32 v[4:5], v[4:5], v[16:17], v[18:19]
	v_mul_f32_e32 v20, v4, v20
	v_mul_f32_e32 v21, v5, v21
	v_cvt_pk_bf16_f32 v20, v20, v21
	global_store_dword v3, v20, s[18:19]
	s_add_u32 s18, s18, 0x1800
	s_addc_u32 s19, s19, 0
	global_load_dwordx2 v[42:43], v2, s[12:13] nt
	global_load_dword v69, v3, s[14:15] nt
	s_add_u32 s12, s12, 0x2000
	s_addc_u32 s13, s13, 0
	s_add_u32 s14, s14, 0x1000
	s_addc_u32 s15, s15, 0
	s_waitcnt vmcnt(45)
	v_lshlrev_b32_e32 v8, 16, v44
	v_lshlrev_b32_e32 v9, 16, v45
	v_exp_f32_e32 v8, v8
	v_exp_f32_e32 v9, v9
	v_and_b32_e32 v10, 0xffff0000, v44
	v_and_b32_e32 v11, 0xffff0000, v45
	v_lshlrev_b32_e32 v12, 16, v70
	v_and_b32_e32 v13, 0xffff0000, v70
	v_pk_fma_f32 v[4:5], v[4:5], v[8:9], v[10:11]
	v_mul_f32_e32 v12, v4, v12
	v_mul_f32_e32 v13, v5, v13
	v_cvt_pk_bf16_f32 v12, v12, v13
	global_store_dword v3, v12, s[18:19]
	s_add_u32 s18, s18, 0x1800
	s_addc_u32 s19, s19, 0
	global_load_dwordx2 v[44:45], v2, s[12:13] nt
	global_load_dword v70, v3, s[14:15] nt
	s_add_u32 s12, s12, 0x2000
	s_addc_u32 s13, s13, 0
	s_add_u32 s14, s14, 0x1000
	s_addc_u32 s15, s15, 0
	s_waitcnt vmcnt(45)
	v_lshlrev_b32_e32 v16, 16, v46
	v_lshlrev_b32_e32 v17, 16, v47
	v_exp_f32_e32 v16, v16
	v_exp_f32_e32 v17, v17
	v_and_b32_e32 v18, 0xffff0000, v46
	v_and_b32_e32 v19, 0xffff0000, v47
	v_lshlrev_b32_e32 v20, 16, v71
	v_and_b32_e32 v21, 0xffff0000, v71
	v_pk_fma_f32 v[4:5], v[4:5], v[16:17], v[18:19]
	v_mul_f32_e32 v20, v4, v20
	v_mul_f32_e32 v21, v5, v21
	v_cvt_pk_bf16_f32 v20, v20, v21
	global_store_dword v3, v20, s[18:19]
	s_add_u32 s18, s18, 0x1800
	s_addc_u32 s19, s19, 0
	global_load_dwordx2 v[46:47], v2, s[12:13] nt
	global_load_dword v71, v3, s[14:15] nt
	s_add_u32 s12, s12, 0x2000
	s_addc_u32 s13, s13, 0
	s_add_u32 s14, s14, 0x1000
	s_addc_u32 s15, s15, 0
	s_waitcnt vmcnt(45)
; __device__ __forceinline__ unsigned cvt_pk_bf16(float lo, float hi) { unsigned r; asm volatile("v_cvt_pk_bf16_f32 %0, %1, %2" : "=v"(r) : "v"(lo), "v"(hi)); return r; }
; __device__ __forceinline__ float bf_lo(unsigned w) { return __uint_as_float(w << 16); }
; __device__ __forceinline__ float bf_hi(unsigned w) { return __uint_as_float(w & 0xffff0000u); }
; __global__ void __launch_bounds__(NTHR, 2) hybrid_block_fwd(Args a) {
;     ...
;         for (int i = 0; i < CH_L; ++i) {
;             const u32x2 q = pab[(size_t)i * (LW / 2)]; const f32x2 av = (f32x2){__builtin_amdgcn_exp2f(bf_lo(q.x)), __builtin_amdgcn_exp2f(bf_lo(q.y))}, bv = (f32x2){bf_hi(q.x), bf_hi(q.y)}; const unsigned gq = pg[(size_t)i * (LW / 2)];
;             H = av * H + bv;
;             po[(size_t)i * (KC / 2)] = cvt_pk_bf16(H.x * bf_lo(gq), H.y * bf_hi(gq));
;         }
	v_lshlrev_b32_e32 v8, 16, v48
	v_lshlrev_b32_e32 v9, 16, v49
	v_exp_f32_e32 v8, v8
	v_exp_f32_e32 v9, v9
	v_and_b32_e32 v10, 0xffff0000, v48
	v_and_b32_e32 v11, 0xffff0000, v49
	v_lshlrev_b32_e32 v12, 16, v72
	v_and_b32_e32 v13, 0xffff0000, v72
	v_pk_fma_f32 v[4:5], v[4:5], v[8:9], v[10:11]
	v_mul_f32_e32 v12, v4, v12
	v_mul_f32_e32 v13, v5, v13
	v_cvt_pk_bf16_f32 v12, v12, v13
	global_store_dword v3, v12, s[18:19]
	s_add_u32 s18, s18, 0x1800
	s_addc_u32 s19, s19, 0
	global_load_dwordx2 v[48:49], v2, s[12:13] nt
	global_load_dword v72, v3, s[14:15] nt
	s_add_u32 s12, s12, 0x2000
	s_addc_u32 s13, s13, 0
	s_add_u32 s14, s14, 0x1000
	s_addc_u32 s15, s15, 0
	s_waitcnt vmcnt(45)
	v_lshlrev_b32_e32 v16, 16, v50
	v_lshlrev_b32_e32 v17, 16, v51
	v_exp_f32_e32 v16, v16
	v_exp_f32_e32 v17, v17
	v_and_b32_e32 v18, 0xffff0000, v50
	v_and_b32_e32 v19, 0xffff0000, v51
	v_lshlrev_b32_e32 v20, 16, v73
	v_and_b32_e32 v21, 0xffff0000, v73
	v_pk_fma_f32 v[4:5], v[4:5], v[16:17], v[18:19]
	v_mul_f32_e32 v20, v4, v20
	v_mul_f32_e32 v21, v5, v21
	v_cvt_pk_bf16_f32 v20, v20, v21
	global_store_dword v3, v20, s[18:19]
	s_add_u32 s18, s18, 0x1800
	s_addc_u32 s19, s19, 0
	global_load_dwordx2 v[50:51], v2, s[12:13] nt
	global_load_dword v73, v3, s[14:15] nt
	s_add_u32 s12, s12, 0x2000
	s_addc_u32 s13, s13, 0
	s_add_u32 s14, s14, 0x1000
	s_addc_u32 s15, s15, 0
	s_waitcnt vmcnt(45)
	v_lshlrev_b32_e32 v8, 16, v52
	v_lshlrev_b32_e32 v9, 16, v53
	v_exp_f32_e32 v8, v8
	v_exp_f32_e32 v9, v9
	v_and_b32_e32 v10, 0xffff0000, v52
	v_and_b32_e32 v11, 0xffff0000, v53
	v_lshlrev_b32_e32 v12, 16, v74
	v_and_b32_e32 v13, 0xffff0000, v74
	v_pk_fma_f32 v[4:5], v[4:5], v[8:9], v[10:11]
	v_mul_f32_e32 v12, v4, v12
	v_mul_f32_e32 v13, v5, v13
	v_cvt_pk_bf16_f32 v12, v12, v13
	global_store_dword v3, v12, s[18:19]
	s_add_u32 s18, s18, 0x1800
	s_addc_u32 s19, s19, 0
	global_load_dwordx2 v[52:53], v2, s[12:13] nt
	global_load_dword v74, v3, s[14:15] nt
	s_add_u32 s12, s12, 0x2000
	s_addc_u32 s13, s13, 0
	s_add_u32 s14, s14, 0x1000
	s_addc_u32 s15, s15, 0
	s_waitcnt vmcnt(45)
	v_lshlrev_b32_e32 v16, 16, v54
	v_lshlrev_b32_e32 v17, 16, v55
	v_exp_f32_e32 v16, v16
	v_exp_f32_e32 v17, v17
	v_and_b32_e32 v18, 0xffff0000, v54
	v_and_b32_e32 v19, 0xffff0000, v55
	v_lshlrev_b32_e32 v20, 16, v75
	v_and_b32_e32 v21, 0xffff0000, v75
	v_pk_fma_f32 v[4:5], v[4:5], v[16:17], v[18:19]
	v_mul_f32_e32 v20, v4, v20
	v_mul_f32_e32 v21, v5, v21
	v_cvt_pk_bf16_f32 v20, v20, v21
	global_store_dword v3, v20, s[18:19]
	s_add_u32 s18, s18, 0x1800
	s_addc_u32 s19, s19, 0
	global_load_dwordx2 v[54:55], v2, s[12:13] nt
	global_load_dword v75, v3, s[14:15] nt
	s_add_u32 s12, s12, 0x2000
	s_addc_u32 s13, s13, 0
	s_add_u32 s14, s14, 0x1000
	s_addc_u32 s15, s15, 0
	s_waitcnt vmcnt(45)
	v_lshlrev_b32_e32 v8, 16, v56
	v_lshlrev_b32_e32 v9, 16, v57
	v_exp_f32_e32 v8, v8
	v_exp_f32_e32 v9, v9
	v_and_b32_e32 v10, 0xffff0000, v56
	v_and_b32_e32 v11, 0xffff0000, v57
	v_lshlrev_b32_e32 v12, 16, v76
	v_and_b32_e32 v13, 0xffff0000, v76
	v_pk_fma_f32 v[4:5], v[4:5], v[8:9], v[10:11]
	v_mul_f32_e32 v12, v4, v12
	v_mul_f32_e32 v13, v5, v13
	v_cvt_pk_bf16_f32 v12, v12, v13
	global_store_dword v3, v12, s[18:19]
	s_add_u32 s18, s18, 0x1800
	s_addc_u32 s19, s19, 0
	global_load_dwordx2 v[56:57], v2, s[12:13] nt
	global_load_dword v76, v3, s[14:15] nt
	s_add_u32 s12, s12, 0x2000
	s_addc_u32 s13, s13, 0
	s_add_u32 s14, s14, 0x1000
	s_addc_u32 s15, s15, 0
	s_waitcnt vmcnt(45)
	v_lshlrev_b32_e32 v16, 16, v58
	v_lshlrev_b32_e32 v17, 16, v59
	v_exp_f32_e32 v16, v16
	v_exp_f32_e32 v17, v17
	v_and_b32_e32 v18, 0xffff0000, v58
	v_and_b32_e32 v19, 0xffff0000, v59
	v_lshlrev_b32_e32 v20, 16, v77
	v_and_b32_e32 v21, 0xffff0000, v77
	v_pk_fma_f32 v[4:5], v[4:5], v[16:17], v[18:19]
	v_mul_f32_e32 v20, v4, v20
	v_mul_f32_e32 v21, v5, v21
	v_cvt_pk_bf16_f32 v20, v20, v21
	global_store_dword v3, v20, s[18:19]
	s_add_u32 s18, s18, 0x1800
	s_addc_u32 s19, s19, 0
	global_load_dwordx2 v[58:59], v2, s[12:13] nt
	global_load_dword v77, v3, s[14:15] nt
	s_add_u32 s12, s12, 0x2000
	s_addc_u32 s13, s13, 0
	s_add_u32 s14, s14, 0x1000
	s_addc_u32 s15, s15, 0
	s_waitcnt vmcnt(45)
	v_lshlrev_b32_e32 v8, 16, v60
	v_lshlrev_b32_e32 v9, 16, v61
	v_exp_f32_e32 v8, v8
	v_exp_f32_e32 v9, v9
	v_and_b32_e32 v10, 0xffff0000, v60
	v_and_b32_e32 v11, 0xffff0000, v61
	v_lshlrev_b32_e32 v12, 16, v78
	v_and_b32_e32 v13, 0xffff0000, v78
	v_pk_fma_f32 v[4:5], v[4:5], v[8:9], v[10:11]
	v_mul_f32_e32 v12, v4, v12
	v_mul_f32_e32 v13, v5, v13
	v_cvt_pk_bf16_f32 v12, v12, v13
	global_store_dword v3, v12, s[18:19]
	s_add_u32 s18, s18, 0x1800
	s_addc_u32 s19, s19, 0
	global_load_dwordx2 v[60:61], v2, s[12:13] nt
	global_load_dword v78, v3, s[14:15] nt
	s_add_u32 s12, s12, 0x2000
	s_addc_u32 s13, s13, 0
	s_add_u32 s14, s14, 0x1000
	s_addc_u32 s15, s15, 0
	s_waitcnt vmcnt(45)
	v_lshlrev_b32_e32 v16, 16, v62
	v_lshlrev_b32_e32 v17, 16, v63
	v_exp_f32_e32 v16, v16
	v_exp_f32_e32 v17, v17
	v_and_b32_e32 v18, 0xffff0000, v62
	v_and_b32_e32 v19, 0xffff0000, v63
	v_lshlrev_b32_e32 v20, 16, v79
	v_and_b32_e32 v21, 0xffff0000, v79
	v_pk_fma_f32 v[4:5], v[4:5], v[16:17], v[18:19]
	v_mul_f32_e32 v20, v4, v20
	v_mul_f32_e32 v21, v5, v21
	v_cvt_pk_bf16_f32 v20, v20, v21
	global_store_dword v3, v20, s[18:19]
	s_add_u32 s18, s18, 0x1800
	s_addc_u32 s19, s19, 0
	global_load_dwordx2 v[62:63], v2, s[12:13] nt
	global_load_dword v79, v3, s[14:15] nt
	s_add_u32 s12, s12, 0x2000
	s_addc_u32 s13, s13, 0
	s_add_u32 s14, s14, 0x1000
	s_addc_u32 s15, s15, 0
	s_sub_u32 s22, s22, 1
	s_cmp_lg_u32 s22, 0
	s_cbranch_scc1 .Lp2d_steady
; __device__ __forceinline__ unsigned cvt_pk_bf16(float lo, float hi) { unsigned r; asm volatile("v_cvt_pk_bf16_f32 %0, %1, %2" : "=v"(r) : "v"(lo), "v"(hi)); return r; }
; __device__ __forceinline__ float bf_lo(unsigned w) { return __uint_as_float(w << 16); }
; __device__ __forceinline__ float bf_hi(unsigned w) { return __uint_as_float(w & 0xffff0000u); }
; __global__ void __launch_bounds__(NTHR, 2) hybrid_block_fwd(Args a) {
;     ...
;         for (int i = 0; i < CH_L; ++i) {
;             const u32x2 q = pab[(size_t)i * (LW / 2)]; const f32x2 av = (f32x2){__builtin_amdgcn_exp2f(bf_lo(q.x)), __builtin_amdgcn_exp2f(bf_lo(q.y))}, bv = (f32x2){bf_hi(q.x), bf_hi(q.y)}; const unsigned gq = pg[(size_t)i * (LW / 2)];
;             H = av * H + bv;
;             po[(size_t)i * (KC / 2)] = cvt_pk_bf16(H.x * bf_lo(gq), H.y * bf_hi(gq));
;         }
	s_waitcnt vmcnt(45)
	v_lshlrev_b32_e32 v8, 16, v32
	v_lshlrev_b32_e32 v9, 16, v33
	v_exp_f32_e32 v8, v8
	v_exp_f32_e32 v9, v9
	v_and_b32_e32 v10, 0xffff0000, v32
	v_and_b32_e32 v11, 0xffff0000, v33
	v_lshlrev_b32_e32 v12, 16, v64
	v_and_b32_e32 v13, 0xffff0000, v64
	v_pk_fma_f32 v[4:5], v[4:5], v[8:9], v[10:11]
	v_mul_f32_e32 v12, v4, v12
	v_mul_f32_e32 v13, v5, v13
	v_cvt_pk_bf16_f32 v12, v12, v13
	global_store_dword v3, v12, s[18:19]
	s_add_u32 s18, s18, 0x1800
	s_addc_u32 s19, s19, 0
	s_waitcnt vmcnt(43)
	v_lshlrev_b32_e32 v16, 16, v34
	v_lshlrev_b32_e32 v17, 16, v35
	v_exp_f32_e32 v16, v16
	v_exp_f32_e32 v17, v17
	v_and_b32_e32 v18, 0xffff0000, v34
	v_and_b32_e32 v19, 0xffff0000, v35
	v_lshlrev_b32_e32 v20, 16, v65
	v_and_b32_e32 v21, 0xffff0000, v65
	v_pk_fma_f32 v[4:5], v[4:5], v[16:17], v[18:19]
	v_mul_f32_e32 v20, v4, v20
	v_mul_f32_e32 v21, v5, v21
	v_cvt_pk_bf16_f32 v20, v20, v21
	global_store_dword v3, v20, s[18:19]
	s_add_u32 s18, s18, 0x1800
	s_addc_u32 s19, s19, 0
	s_waitcnt vmcnt(41)
	v_lshlrev_b32_e32 v8, 16, v36
	v_lshlrev_b32_e32 v9, 16, v37
	v_exp_f32_e32 v8, v8
	v_exp_f32_e32 v9, v9
	v_and_b32_e32 v10, 0xffff0000, v36
	v_and_b32_e32 v11, 0xffff0000, v37
	v_lshlrev_b32_e32 v12, 16, v66
	v_and_b32_e32 v13, 0xffff0000, v66
	v_pk_fma_f32 v[4:5], v[4:5], v[8:9], v[10:11]
	v_mul_f32_e32 v12, v4, v12
	v_mul_f32_e32 v13, v5, v13
	v_cvt_pk_bf16_f32 v12, v12, v13
	global_store_dword v3, v12, s[18:19]
	s_add_u32 s18, s18, 0x1800
	s_addc_u32 s19, s19, 0
	s_waitcnt vmcnt(39)
	v_lshlrev_b32_e32 v16, 16, v38
	v_lshlrev_b32_e32 v17, 16, v39
	v_exp_f32_e32 v16, v16
	v_exp_f32_e32 v17, v17
	v_and_b32_e32 v18, 0xffff0000, v38
	v_and_b32_e32 v19, 0xffff0000, v39
	v_lshlrev_b32_e32 v20, 16, v67
	v_and_b32_e32 v21, 0xffff0000, v67
	v_pk_fma_f32 v[4:5], v[4:5], v[16:17], v[18:19]
	v_mul_f32_e32 v20, v4, v20
	v_mul_f32_e32 v21, v5, v21
	v_cvt_pk_bf16_f32 v20, v20, v21
	global_store_dword v3, v20, s[18:19]
	s_add_u32 s18, s18, 0x1800
	s_addc_u32 s19, s19, 0
	s_waitcnt vmcnt(37)
	v_lshlrev_b32_e32 v8, 16, v40
	v_lshlrev_b32_e32 v9, 16, v41
	v_exp_f32_e32 v8, v8
	v_exp_f32_e32 v9, v9
	v_and_b32_e32 v10, 0xffff0000, v40
	v_and_b32_e32 v11, 0xffff0000, v41
	v_lshlrev_b32_e32 v12, 16, v68
	v_and_b32_e32 v13, 0xffff0000, v68
	v_pk_fma_f32 v[4:5], v[4:5], v[8:9], v[10:11]
	v_mul_f32_e32 v12, v4, v12
	v_mul_f32_e32 v13, v5, v13
	v_cvt_pk_bf16_f32 v12, v12, v13
	global_store_dword v3, v12, s[18:19]
	s_add_u32 s18, s18, 0x1800
	s_addc_u32 s19, s19, 0
	s_waitcnt vmcnt(35)
	v_lshlrev_b32_e32 v16, 16, v42
	v_lshlrev_b32_e32 v17, 16, v43
	v_exp_f32_e32 v16, v16
	v_exp_f32_e32 v17, v17
	v_and_b32_e32 v18, 0xffff0000, v42
	v_and_b32_e32 v19, 0xffff0000, v43
	v_lshlrev_b32_e32 v20, 16, v69
	v_and_b32_e32 v21, 0xffff0000, v69
	v_pk_fma_f32 v[4:5], v[4:5], v[16:17], v[18:19]
	v_mul_f32_e32 v20, v4, v20
	v_mul_f32_e32 v21, v5, v21
	v_cvt_pk_bf16_f32 v20, v20, v21
	global_store_dword v3, v20, s[18:19]
	s_add_u32 s18, s18, 0x1800
	s_addc_u32 s19, s19, 0
	s_waitcnt vmcnt(33)
	v_lshlrev_b32_e32 v8, 16, v44
	v_lshlrev_b32_e32 v9, 16, v45
	v_exp_f32_e32 v8, v8
	v_exp_f32_e32 v9, v9
	v_and_b32_e32 v10, 0xffff0000, v44
	v_and_b32_e32 v11, 0xffff0000, v45
	v_lshlrev_b32_e32 v12, 16, v70
	v_and_b32_e32 v13, 0xffff0000, v70
	v_pk_fma_f32 v[4:5], v[4:5], v[8:9], v[10:11]
	v_mul_f32_e32 v12, v4, v12
	v_mul_f32_e32 v13, v5, v13
	v_cvt_pk_bf16_f32 v12, v12, v13
	global_store_dword v3, v12, s[18:19]
	s_add_u32 s18, s18, 0x1800
	s_addc_u32 s19, s19, 0
	s_waitcnt vmcnt(31)
	v_lshlrev_b32_e32 v16, 16, v46
	v_lshlrev_b32_e32 v17, 16, v47
	v_exp_f32_e32 v16, v16
	v_exp_f32_e32 v17, v17
	v_and_b32_e32 v18, 0xffff0000, v46
	v_and_b32_e32 v19, 0xffff0000, v47
	v_lshlrev_b32_e32 v20, 16, v71
	v_and_b32_e32 v21, 0xffff0000, v71
	v_pk_fma_f32 v[4:5], v[4:5], v[16:17], v[18:19]
	v_mul_f32_e32 v20, v4, v20
	v_mul_f32_e32 v21, v5, v21
	v_cvt_pk_bf16_f32 v20, v20, v21
	global_store_dword v3, v20, s[18:19]
	s_add_u32 s18, s18, 0x1800
	s_addc_u32 s19, s19, 0
	s_waitcnt vmcnt(29)
	v_lshlrev_b32_e32 v8, 16, v48
	v_lshlrev_b32_e32 v9, 16, v49
	v_exp_f32_e32 v8, v8
	v_exp_f32_e32 v9, v9
	v_and_b32_e32 v10, 0xffff0000, v48
	v_and_b32_e32 v11, 0xffff0000, v49
	v_lshlrev_b32_e32 v12, 16, v72
	v_and_b32_e32 v13, 0xffff0000, v72
	v_pk_fma_f32 v[4:5], v[4:5], v[8:9], v[10:11]
	v_mul_f32_e32 v12, v4, v12
	v_mul_f32_e32 v13, v5, v13
	v_cvt_pk_bf16_f32 v12, v12, v13
	global_store_dword v3, v12, s[18:19]
	s_add_u32 s18, s18, 0x1800
	s_addc_u32 s19, s19, 0
	s_waitcnt vmcnt(27)
	v_lshlrev_b32_e32 v16, 16, v50
	v_lshlrev_b32_e32 v17, 16, v51
	v_exp_f32_e32 v16, v16
	v_exp_f32_e32 v17, v17
	v_and_b32_e32 v18, 0xffff0000, v50
	v_and_b32_e32 v19, 0xffff0000, v51
	v_lshlrev_b32_e32 v20, 16, v73
	v_and_b32_e32 v21, 0xffff0000, v73
	v_pk_fma_f32 v[4:5], v[4:5], v[16:17], v[18:19]
	v_mul_f32_e32 v20, v4, v20
	v_mul_f32_e32 v21, v5, v21
	v_cvt_pk_bf16_f32 v20, v20, v21
	global_store_dword v3, v20, s[18:19]
	s_add_u32 s18, s18, 0x1800
	s_addc_u32 s19, s19, 0
	s_waitcnt vmcnt(25)
; __device__ __forceinline__ unsigned cvt_pk_bf16(float lo, float hi) { unsigned r; asm volatile("v_cvt_pk_bf16_f32 %0, %1, %2" : "=v"(r) : "v"(lo), "v"(hi)); return r; }
; __device__ __forceinline__ float bf_lo(unsigned w) { return __uint_as_float(w << 16); }
; __device__ __forceinline__ float bf_hi(unsigned w) { return __uint_as_float(w & 0xffff0000u); }
; __device__ __forceinline__ unsigned xb_ld(unsigned* p)              { return __hip_atomic_load(p, __ATOMIC_RELAXED, __HIP_MEMORY_SCOPE_AGENT); }
; __device__ __forceinline__ void xcd_barrier_complete(unsigned* bar, unsigned x, unsigned& nloc, unsigned& nx) {
;     const unsigned G = gridDim.x * gridDim.y * gridDim.z;
;     unsigned sum, cnt, mine, sp = 0u;
;     for (;;) {
;         sum = 0u; cnt = 0u; mine = 0u;
; #pragma unroll
;         for (unsigned j = 0; j < 16; ++j) { const unsigned c = xb_ld(&bar[XB_XCNT(j)]); sum += c; cnt += (c > 0u) ? 1u : 0u; mine = (j == x) ? c : mine; }
;         if (sum == G) break;
;         __builtin_amdgcn_s_sleep(1);
;         if ((++sp & 255u) == 0u) { if (xb_ld(&bar[XB_TMO])) break; if (sp > XB_SPIN_CAP) { atomicAdd(&bar[XB_TMO], 1u); break; } }
;     }
;     nloc = mine > 0u ? mine : 1u; nx = cnt > 0u ? cnt : 1u;
; }
; __device__ __forceinline__ void xcd_barrier(const XcdBarrier& b) {
;     asm volatile("s_waitcnt vmcnt(0)" ::: "memory");
;     __syncthreads();
;     if (threadIdx.x == 0) {
;         unsigned* bar = b.bar;
;         __builtin_amdgcn_s_waitcnt(0);
;         unsigned nloc = b.st[0], nx = b.st[1];
;         if (nloc == 0u) { xcd_barrier_complete(bar, b.x, nloc, nx); b.st[0] = nloc; b.st[1] = nx; }
; __global__ void __launch_bounds__(NTHR, 2) hybrid_block_fwd(Args a) {
;     ...
;         for (int i = 0; i < CH_L; ++i) {
;             const u32x2 q = pab[(size_t)i * (LW / 2)]; const f32x2 av = (f32x2){__builtin_amdgcn_exp2f(bf_lo(q.x)), __builtin_amdgcn_exp2f(bf_lo(q.y))}, bv = (f32x2){bf_hi(q.x), bf_hi(q.y)}; const unsigned gq = pg[(size_t)i * (LW / 2)];
;             H = av * H + bv;
;             po[(size_t)i * (KC / 2)] = cvt_pk_bf16(H.x * bf_lo(gq), H.y * bf_hi(gq));
;         }
	v_lshlrev_b32_e32 v8, 16, v52
	v_lshlrev_b32_e32 v9, 16, v53
	v_exp_f32_e32 v8, v8
	v_exp_f32_e32 v9, v9
	v_and_b32_e32 v10, 0xffff0000, v52
	v_and_b32_e32 v11, 0xffff0000, v53
	v_lshlrev_b32_e32 v12, 16, v74
	v_and_b32_e32 v13, 0xffff0000, v74
	v_pk_fma_f32 v[4:5], v[4:5], v[8:9], v[10:11]
	v_mul_f32_e32 v12, v4, v12
	v_mul_f32_e32 v13, v5, v13
	v_cvt_pk_bf16_f32 v12, v12, v13
	global_store_dword v3, v12, s[18:19]
	s_add_u32 s18, s18, 0x1800
	s_addc_u32 s19, s19, 0
	s_waitcnt vmcnt(23)
	v_lshlrev_b32_e32 v16, 16, v54
	v_lshlrev_b32_e32 v17, 16, v55
	v_exp_f32_e32 v16, v16
	v_exp_f32_e32 v17, v17
	v_and_b32_e32 v18, 0xffff0000, v54
	v_and_b32_e32 v19, 0xffff0000, v55
	v_lshlrev_b32_e32 v20, 16, v75
	v_and_b32_e32 v21, 0xffff0000, v75
	v_pk_fma_f32 v[4:5], v[4:5], v[16:17], v[18:19]
	v_mul_f32_e32 v20, v4, v20
	v_mul_f32_e32 v21, v5, v21
	v_cvt_pk_bf16_f32 v20, v20, v21
	global_store_dword v3, v20, s[18:19]
	s_add_u32 s18, s18, 0x1800
	s_addc_u32 s19, s19, 0
	s_waitcnt vmcnt(21)
	v_lshlrev_b32_e32 v8, 16, v56
	v_lshlrev_b32_e32 v9, 16, v57
	v_exp_f32_e32 v8, v8
	v_exp_f32_e32 v9, v9
	v_and_b32_e32 v10, 0xffff0000, v56
	v_and_b32_e32 v11, 0xffff0000, v57
	v_lshlrev_b32_e32 v12, 16, v76
	v_and_b32_e32 v13, 0xffff0000, v76
	v_pk_fma_f32 v[4:5], v[4:5], v[8:9], v[10:11]
	v_mul_f32_e32 v12, v4, v12
	v_mul_f32_e32 v13, v5, v13
	v_cvt_pk_bf16_f32 v12, v12, v13
	global_store_dword v3, v12, s[18:19]
	s_add_u32 s18, s18, 0x1800
	s_addc_u32 s19, s19, 0
	s_waitcnt vmcnt(19)
	v_lshlrev_b32_e32 v16, 16, v58
	v_lshlrev_b32_e32 v17, 16, v59
	v_exp_f32_e32 v16, v16
	v_exp_f32_e32 v17, v17
	v_and_b32_e32 v18, 0xffff0000, v58
	v_and_b32_e32 v19, 0xffff0000, v59
	v_lshlrev_b32_e32 v20, 16, v77
	v_and_b32_e32 v21, 0xffff0000, v77
	v_pk_fma_f32 v[4:5], v[4:5], v[16:17], v[18:19]
	v_mul_f32_e32 v20, v4, v20
	v_mul_f32_e32 v21, v5, v21
	v_cvt_pk_bf16_f32 v20, v20, v21
	global_store_dword v3, v20, s[18:19]
	s_add_u32 s18, s18, 0x1800
	s_addc_u32 s19, s19, 0
	s_waitcnt vmcnt(17)
	v_lshlrev_b32_e32 v8, 16, v60
	v_lshlrev_b32_e32 v9, 16, v61
	v_exp_f32_e32 v8, v8
	v_exp_f32_e32 v9, v9
	v_and_b32_e32 v10, 0xffff0000, v60
	v_and_b32_e32 v11, 0xffff0000, v61
	v_lshlrev_b32_e32 v12, 16, v78
	v_and_b32_e32 v13, 0xffff0000, v78
	v_pk_fma_f32 v[4:5], v[4:5], v[8:9], v[10:11]
	v_mul_f32_e32 v12, v4, v12
	v_mul_f32_e32 v13, v5, v13
	v_cvt_pk_bf16_f32 v12, v12, v13
	global_store_dword v3, v12, s[18:19]
	s_add_u32 s18, s18, 0x1800
	s_addc_u32 s19, s19, 0
	s_waitcnt vmcnt(15)
	v_lshlrev_b32_e32 v16, 16, v62
	v_lshlrev_b32_e32 v17, 16, v63
	v_exp_f32_e32 v16, v16
	v_exp_f32_e32 v17, v17
	v_and_b32_e32 v18, 0xffff0000, v62
	v_and_b32_e32 v19, 0xffff0000, v63
	v_lshlrev_b32_e32 v20, 16, v79
	v_and_b32_e32 v21, 0xffff0000, v79
	v_pk_fma_f32 v[4:5], v[4:5], v[16:17], v[18:19]
	v_mul_f32_e32 v20, v4, v20
	v_mul_f32_e32 v21, v5, v21
	v_cvt_pk_bf16_f32 v20, v20, v21
	global_store_dword v3, v20, s[18:19]
	s_add_u32 s18, s18, 0x1800
	s_addc_u32 s19, s19, 0
	s_waitcnt vmcnt(0)
	s_barrier
	s_mov_b64 s[0:1], exec
	v_readlane_b32 s4, v248, 6
	v_readlane_b32 s5, v248, 7
	s_and_b64 s[4:5], s[0:1], s[4:5]
	s_mov_b64 exec, s[4:5]
	s_cbranch_execz .LBB0_735
	s_add_i32 s4, 0, 0x20020
	v_mov_b32_e32 v0, s4
	s_waitcnt vmcnt(0) expcnt(0) lgkmcnt(0)
	ds_read_b32 v2, v0
	s_add_i32 s4, 0, 0x20024
	v_mov_b32_e32 v0, s4
	ds_read_b32 v0, v0
	s_waitcnt lgkmcnt(1)
	v_cmp_ne_u32_e32 vcc, 0, v2
	s_cbranch_vccnz .LBB0_699
	v_readlane_b32 s4, v248, 2
	v_readlane_b32 s5, v248, 3
	v_readlane_b32 s8, v248, 1
	s_mul_i32 s18, s5, s8
	s_mul_i32 s18, s18, s4
	s_add_u32 s4, s94, 0x40200
	s_addc_u32 s5, s95, 0
	s_add_u32 s8, s94, 0x40400
	s_addc_u32 s9, s95, 0
	s_add_u32 s10, s94, 0x40500
	s_addc_u32 s11, s95, 0
	s_add_u32 s38, s94, 0x40600
	s_addc_u32 s39, s95, 0
	s_add_u32 s42, s94, 0x40700
	s_addc_u32 s43, s95, 0
	s_add_u32 s54, s94, 0x40800
	s_addc_u32 s55, s95, 0
	s_add_u32 s56, s94, 0x40900
	s_addc_u32 s57, s95, 0
	s_add_u32 s58, s94, 0x40a00
	s_addc_u32 s59, s95, 0
	s_add_u32 s60, s94, 0x40b00
	s_addc_u32 s61, s95, 0
	s_add_u32 s62, s94, 0x40c00
	s_addc_u32 s63, s95, 0
	s_add_u32 s64, s94, 0x40d00
	s_addc_u32 s65, s95, 0
	s_add_u32 s66, s94, 0x40e00
	s_addc_u32 s67, s95, 0
	s_add_u32 s70, s94, 0x40f00
	s_addc_u32 s71, s95, 0
	s_add_u32 s72, s94, 0x41000
	s_addc_u32 s73, s95, 0
	s_add_u32 s74, s94, 0x41100
	s_addc_u32 s75, s95, 0
	s_add_u32 s34, s94, 0x41200
	s_addc_u32 s35, s95, 0
	s_add_u32 s48, s94, 0x41300
	s_addc_u32 s49, s95, 0
	s_mov_b32 s19, 1
	v_mov_b32_e32 v16, 0
	s_branch .LBB0_687
